# prompt-attention unit: K/V staging loads issued together (was four load-wait-write steps in series)
# speedup vs baseline: 1.0087x; 1.0024x over previous
; __device__ __forceinline__ void attn_prompt_unit(unsigned char* lds, const bf16_t* Q, const bf16_t* Kb, const bf16_t* Vb, bf16_t* MIX, const float* sinks, int unit, int tid) {
;     ...
;     __syncthreads();
; #pragma unroll
;     for (int i = 0; i < 4; ++i) { const int ch = tid + 512 * i, kj = ch >> 3, c8 = ch & 7; const int tok = nb * 128 - 128 + kj;
;         u32x4 kv = (u32x4){0u, 0u, 0u, 0u}, vv = kv;
;         if (tok >= 0) { const size_t off = ((size_t)b * SEQ + tok) * 128 + kvh * 64 + c8 * 8; kv = *(const u32x4*)(Kb + off); vv = *(const u32x4*)(Vb + off); }
;         *(u32x4*)(lds + ATT_KS + kj * KS_PITCH + c8 * 16) = kv;
;         bf16_t* vt = (bf16_t*)(lds + ATT_VT) + kj;
; #pragma unroll
;         for (int j = 0; j < 4; ++j) { const unsigned w = vv[j]; vt[(size_t)(c8 * 8 + 2 * j) * (VT_PITCH / 2)] = (bf16_t)(w & 0xffffu); vt[(size_t)(c8 * 8 + 2 * j + 1) * (VT_PITCH / 2)] = (bf16_t)(w >> 16); } }
;     __syncthreads();
.LBB0_928:
	s_bfe_u32 s8, s15, 0x50001
	s_ashr_i32 s0, s15, 6
	s_and_b32 s9, s15, 1
	s_lshl_b32 s10, s8, 7
	s_ashr_i32 s1, s0, 31
	s_add_i32 s11, s10, 0xffffff80
	s_lshl_b64 s[6:7], s[0:1], 19
	s_lshl_b32 s16, s9, 6
	s_or_b32 s6, s6, s16
	v_mov_b32_e32 v15, s7
	v_or_b32_e32 v14, s6, v114
	s_waitcnt vmcnt(0)
	s_barrier
	v_add_u32_e32 v160, s11, v131
	v_cmp_lt_i32_e32 vcc, -1, v160
	v_mov_b32_e32 v16, 0
	v_mov_b32_e32 v17, 0
	v_mov_b32_e32 v18, 0
	v_mov_b32_e32 v19, 0
	v_mov_b32_e32 v20, 0
	v_mov_b32_e32 v21, 0
	v_mov_b32_e32 v22, 0
	v_mov_b32_e32 v23, 0
	s_and_saveexec_b64 s[6:7], vcc
	s_cbranch_execz .Lmy_pst_0
	v_lshlrev_b64 v[2:3], 7, v[160:161]
	v_lshl_add_u64 v[2:3], v[2:3], 0, v[14:15]
	v_lshlrev_b64 v[2:3], 1, v[2:3]
	v_lshl_add_u64 v[6:7], s[4:5], 0, v[2:3]
	v_lshl_add_u64 v[2:3], s[2:3], 0, v[2:3]
	global_load_dwordx4 v[16:19], v[2:3], off
	global_load_dwordx4 v[20:23], v[6:7], off
.Lmy_pst_0:
	s_or_b64 exec, exec, s[6:7]
	v_add_u32_e32 v160, s11, v142
	v_cmp_lt_i32_e32 vcc, -1, v160
	v_mov_b32_e32 v24, 0
	v_mov_b32_e32 v25, 0
	v_mov_b32_e32 v26, 0
	v_mov_b32_e32 v27, 0
	v_mov_b32_e32 v28, 0
	v_mov_b32_e32 v29, 0
	v_mov_b32_e32 v30, 0
	v_mov_b32_e32 v31, 0
	s_and_saveexec_b64 s[6:7], vcc
	s_cbranch_execz .Lmy_pst_1
	v_lshlrev_b64 v[2:3], 7, v[160:161]
	v_lshl_add_u64 v[2:3], v[2:3], 0, v[14:15]
	v_lshlrev_b64 v[2:3], 1, v[2:3]
	v_lshl_add_u64 v[6:7], s[4:5], 0, v[2:3]
	v_lshl_add_u64 v[2:3], s[2:3], 0, v[2:3]
	global_load_dwordx4 v[24:27], v[2:3], off
	global_load_dwordx4 v[28:31], v[6:7], off
.Lmy_pst_1:
	s_or_b64 exec, exec, s[6:7]
	v_add_u32_e32 v160, s11, v143
	v_cmp_lt_i32_e32 vcc, -1, v160
	v_mov_b32_e32 v32, 0
	v_mov_b32_e32 v33, 0
	v_mov_b32_e32 v34, 0
	v_mov_b32_e32 v35, 0
	v_mov_b32_e32 v36, 0
	v_mov_b32_e32 v37, 0
	v_mov_b32_e32 v38, 0
	v_mov_b32_e32 v39, 0
	s_and_saveexec_b64 s[6:7], vcc
	s_cbranch_execz .Lmy_pst_2
	v_lshlrev_b64 v[2:3], 7, v[160:161]
	v_lshl_add_u64 v[2:3], v[2:3], 0, v[14:15]
	v_lshlrev_b64 v[2:3], 1, v[2:3]
	v_lshl_add_u64 v[6:7], s[4:5], 0, v[2:3]
	v_lshl_add_u64 v[2:3], s[2:3], 0, v[2:3]
	global_load_dwordx4 v[32:35], v[2:3], off
	global_load_dwordx4 v[36:39], v[6:7], off
.Lmy_pst_2:
	s_or_b64 exec, exec, s[6:7]
	v_add_u32_e32 v160, s11, v144
	v_cmp_lt_i32_e32 vcc, -1, v160
	v_mov_b32_e32 v40, 0
	v_mov_b32_e32 v41, 0
	v_mov_b32_e32 v42, 0
	v_mov_b32_e32 v43, 0
	v_mov_b32_e32 v44, 0
	v_mov_b32_e32 v45, 0
	v_mov_b32_e32 v46, 0
	v_mov_b32_e32 v47, 0
	s_and_saveexec_b64 s[6:7], vcc
	s_cbranch_execz .Lmy_pst_3
	v_lshlrev_b64 v[2:3], 7, v[160:161]
	v_lshl_add_u64 v[2:3], v[2:3], 0, v[14:15]
	v_lshlrev_b64 v[2:3], 1, v[2:3]
	v_lshl_add_u64 v[6:7], s[4:5], 0, v[2:3]
	v_lshl_add_u64 v[2:3], s[2:3], 0, v[2:3]
	global_load_dwordx4 v[40:43], v[2:3], off
	global_load_dwordx4 v[44:47], v[6:7], off
.Lmy_pst_3:
	s_or_b64 exec, exec, s[6:7]
	s_mov_b32 s16, 0
	s_waitcnt vmcnt(0)
	ds_write_b128 v118, v[16:19]
	ds_write_b16 v119, v20 offset:36864
	ds_write_b16_d16_hi v119, v20 offset:37392
	ds_write_b16 v119, v21 offset:37920
	ds_write_b16_d16_hi v119, v21 offset:38448
	ds_write_b16 v119, v22 offset:38976
	ds_write_b16_d16_hi v119, v22 offset:39504
	ds_write_b16 v119, v23 offset:40032
	ds_write_b16_d16_hi v119, v23 offset:40560
	ds_write_b128 v120, v[24:27]
	ds_write_b16 v122, v28 offset:36864
	ds_write_b16_d16_hi v122, v28 offset:37392
	ds_write_b16 v122, v29 offset:37920
	ds_write_b16_d16_hi v122, v29 offset:38448
	ds_write_b16 v122, v30 offset:38976
	ds_write_b16_d16_hi v122, v30 offset:39504
	ds_write_b16 v122, v31 offset:40032
	ds_write_b16_d16_hi v122, v31 offset:40560
	ds_write_b128 v123, v[32:35]
	ds_write_b16 v124, v36 offset:36864
	ds_write_b16_d16_hi v124, v36 offset:37392
	ds_write_b16 v124, v37 offset:37920
	ds_write_b16_d16_hi v124, v37 offset:38448
	ds_write_b16 v124, v38 offset:38976
	ds_write_b16_d16_hi v124, v38 offset:39504
	ds_write_b16 v124, v39 offset:40032
	ds_write_b16_d16_hi v124, v39 offset:40560
	ds_write_b128 v125, v[40:43]
	ds_write_b16 v126, v44 offset:36864
	ds_write_b16_d16_hi v126, v44 offset:37392
	ds_write_b16 v126, v45 offset:37920
	ds_write_b16_d16_hi v126, v45 offset:38448
	ds_write_b16 v126, v46 offset:38976
	ds_write_b16_d16_hi v126, v46 offset:39504
	ds_write_b16 v126, v47 offset:40032
	ds_write_b16_d16_hi v126, v47 offset:40560
	v_lshl_or_b32 v0, s9, 2, v140
	v_lshlrev_b32_e32 v1, 2, v0
	s_waitcnt lgkmcnt(0)
	s_barrier
	global_load_dword v127, v1, s[26:27]
	s_lshl_b64 s[6:7], s[0:1], 12
	s_or_b32 s6, s6, s10
	v_lshlrev_b32_e32 v160, 7, v0
	s_cmp_lg_u32 s8, 0
	v_lshl_add_u64 v[90:91], v[84:85], 0, v[160:161]
	s_cselect_b64 s[8:9], -1, 0
	v_lshl_add_u64 v[92:93], v[88:89], 0, v[160:161]
	s_mov_b64 s[10:11], -1
